# code placement: the six GEMM K-loop heads aligned to 64 bytes (.p2align 6)
# speedup vs baseline: 1.0012x; 1.0012x over previous
; template <class Epi, class Sched, bool ALIGN_EPI = false, bool SP2 = false>
; __device__ __forceinline__ void gemm_phase(PG8_LAS unsigned char* lds, const Gemm g, const Sched& S, const Epi& E) {
;     ...
;         const bool has_next = S.next(ui + 1, nxt);
;         const char* nA = has_next ? PG8_UA(nxt) : cA; const char* nB = has_next ? PG8_UB(nxt) : cB;
;         for (int t = 0; t < nt; t += 2) {
;             const bool last = (t == nt - 2);
;             const char* a1 = cA + (size_t)(t + 1) * kstep;
;             const char* a2 = last ? nA : cA + (size_t)(t + 2) * kstep; const char* b2 = last ? nB : cB + (size_t)(t + 2) * kstep;
;     ...
; #pragma unroll
;         for (int a = 0; a < 2; ++a)
; #pragma unroll
;             for (int b = 0; b < 2; ++b)
; #pragma unroll
;                 for (int m = 0; m < 4; ++m)
; #pragma unroll
;                     for (int n = 0; n < 2; ++n) acc[a][b][m][n] = (f32x4){0.f, 0.f, 0.f, 0.f};
.LBB0_222:
	s_ashr_i32 s11, s10, 31
	s_lshl_b64 s[38:39], s[10:11], 20
	s_ashr_i32 s9, s8, 31
	v_lshl_add_u64 v[146:147], v[138:139], 0, s[38:39]
	s_lshl_b64 s[38:39], s[8:9], 20
	s_add_u32 s38, s15, s38
	s_addc_u32 s39, s14, s39
	s_and_b64 s[40:41], s[36:37], exec
	s_mov_b64 s[40:41], 0x80080
	v_cndmask_b32_e64 v156, v0, v146, s[36:37]
	s_cselect_b32 s9, s39, s13
	s_cselect_b32 s11, s38, s12
	v_lshl_add_u64 v[148:149], v[0:1], 0, s[40:41]
	s_add_u32 s35, s12, 0x100
	v_mov_b32_e32 v0, 0
	v_cndmask_b32_e64 v155, v1, v147, s[36:37]
	s_addc_u32 s40, s13, 0
	s_mov_b32 s41, -2
	v_mov_b32_e32 v1, v0
	v_mov_b32_e32 v2, v0
	v_mov_b32_e32 v3, v0
	v_mov_b32_e32 v4, v0
	v_mov_b32_e32 v5, v0
	v_mov_b32_e32 v6, v0
	v_mov_b32_e32 v7, v0
	v_mov_b32_e32 v8, v0
	v_mov_b32_e32 v9, v0
	v_mov_b32_e32 v10, v0
	v_mov_b32_e32 v11, v0
	v_mov_b32_e32 v12, v0
	v_mov_b32_e32 v13, v0
	v_mov_b32_e32 v14, v0
	v_mov_b32_e32 v15, v0
	v_mov_b32_e32 v26, v0
	v_mov_b32_e32 v27, v0
	v_mov_b32_e32 v28, v0
	v_mov_b32_e32 v29, v0
	v_mov_b32_e32 v30, v0
	v_mov_b32_e32 v31, v0
	v_mov_b32_e32 v32, v0
	v_mov_b32_e32 v33, v0
	v_mov_b32_e32 v42, v0
	v_mov_b32_e32 v43, v0
	v_mov_b32_e32 v44, v0
	v_mov_b32_e32 v45, v0
	v_mov_b32_e32 v46, v0
	v_mov_b32_e32 v47, v0
	v_mov_b32_e32 v48, v0
	v_mov_b32_e32 v49, v0
	v_mov_b32_e32 v18, v0
	v_mov_b32_e32 v19, v0
	v_mov_b32_e32 v20, v0
	v_mov_b32_e32 v21, v0
	v_mov_b32_e32 v22, v0
	v_mov_b32_e32 v23, v0
	v_mov_b32_e32 v24, v0
	v_mov_b32_e32 v25, v0
	v_mov_b32_e32 v34, v0
	v_mov_b32_e32 v35, v0
	v_mov_b32_e32 v36, v0
	v_mov_b32_e32 v37, v0
	v_mov_b32_e32 v38, v0
	v_mov_b32_e32 v39, v0
	v_mov_b32_e32 v40, v0
	v_mov_b32_e32 v41, v0
	v_mov_b32_e32 v50, v0
	v_mov_b32_e32 v51, v0
	v_mov_b32_e32 v52, v0
	v_mov_b32_e32 v53, v0
	v_mov_b32_e32 v54, v0
	v_mov_b32_e32 v55, v0
	v_mov_b32_e32 v56, v0
	v_mov_b32_e32 v57, v0
	v_mov_b32_e32 v58, v0
	v_mov_b32_e32 v59, v0
	v_mov_b32_e32 v60, v0
	v_mov_b32_e32 v61, v0
	v_mov_b32_e32 v62, v0
	v_mov_b32_e32 v63, v0
	v_mov_b32_e32 v64, v0
	v_mov_b32_e32 v65, v0
	v_mov_b32_e32 v66, v0
	v_mov_b32_e32 v67, v0
	v_mov_b32_e32 v68, v0
	v_mov_b32_e32 v69, v0
	v_mov_b32_e32 v70, v0
	v_mov_b32_e32 v71, v0
	v_mov_b32_e32 v72, v0
	v_mov_b32_e32 v73, v0
	v_mov_b32_e32 v74, v0
	v_mov_b32_e32 v75, v0
	v_mov_b32_e32 v76, v0
	v_mov_b32_e32 v77, v0
	v_mov_b32_e32 v78, v0
	v_mov_b32_e32 v79, v0
	v_mov_b32_e32 v80, v0
	v_mov_b32_e32 v81, v0
	v_mov_b32_e32 v90, v0
	v_mov_b32_e32 v91, v0
	v_mov_b32_e32 v92, v0
	v_mov_b32_e32 v93, v0
	v_mov_b32_e32 v94, v0
	v_mov_b32_e32 v95, v0
	v_mov_b32_e32 v96, v0
	v_mov_b32_e32 v97, v0
	v_mov_b32_e32 v106, v0
	v_mov_b32_e32 v107, v0
	v_mov_b32_e32 v108, v0
	v_mov_b32_e32 v109, v0
	v_mov_b32_e32 v110, v0
	v_mov_b32_e32 v111, v0
	v_mov_b32_e32 v112, v0
	v_mov_b32_e32 v113, v0
	v_mov_b32_e32 v82, v0
	v_mov_b32_e32 v83, v0
	v_mov_b32_e32 v84, v0
	v_mov_b32_e32 v85, v0
	v_mov_b32_e32 v86, v0
	v_mov_b32_e32 v87, v0
	v_mov_b32_e32 v88, v0
	v_mov_b32_e32 v89, v0
	v_mov_b32_e32 v98, v0
	v_mov_b32_e32 v99, v0
	v_mov_b32_e32 v100, v0
	v_mov_b32_e32 v101, v0
	v_mov_b32_e32 v102, v0
	v_mov_b32_e32 v103, v0
	v_mov_b32_e32 v104, v0
	v_mov_b32_e32 v105, v0
	v_mov_b32_e32 v114, v0
	v_mov_b32_e32 v115, v0
	v_mov_b32_e32 v116, v0
	v_mov_b32_e32 v117, v0
	v_mov_b32_e32 v118, v0
	v_mov_b32_e32 v119, v0
	v_mov_b32_e32 v120, v0
	v_mov_b32_e32 v121, v0
	v_mov_b32_e32 v122, v0
	v_mov_b32_e32 v123, v0
	v_mov_b32_e32 v124, v0
	v_mov_b32_e32 v125, v0
	v_mov_b32_e32 v126, v0
	v_mov_b32_e32 v127, v0
	v_mov_b32_e32 v128, v0
	v_mov_b32_e32 v129, v0
	.p2align 6

; template <class Epi, class Sched, bool ALIGN_EPI = false, bool SP2 = false>
; __device__ __forceinline__ void gemm_phase(PG8_LAS unsigned char* lds, const Gemm g, const Sched& S, const Epi& E) {
;     ...
;         const bool has_next = S.next(ui + 1, nxt);
;         const char* nA = has_next ? PG8_UA(nxt) : cA; const char* nB = has_next ? PG8_UB(nxt) : cB;
;         for (int t = 0; t < nt; t += 2) {
;             const bool last = (t == nt - 2);
;             const char* a1 = cA + (size_t)(t + 1) * kstep;
;             const char* a2 = last ? nA : cA + (size_t)(t + 2) * kstep; const char* b2 = last ? nB : cB + (size_t)(t + 2) * kstep;
;     ...
; #pragma unroll
;         for (int a = 0; a < 2; ++a)
; #pragma unroll
;             for (int b = 0; b < 2; ++b)
; #pragma unroll
;                 for (int m = 0; m < 4; ++m)
; #pragma unroll
;                     for (int n = 0; n < 2; ++n) acc[a][b][m][n] = (f32x4){0.f, 0.f, 0.f, 0.f};
.LBB0_1139:
	s_ashr_i32 s9, s8, 31
	s_lshl_b64 s[42:43], s[8:9], 20
	s_add_u32 s42, s61, s42
	s_addc_u32 s43, s78, s43
	s_and_b64 s[44:45], s[40:41], exec
	s_cselect_b32 s5, s43, s37
	s_cselect_b32 s9, s42, s36
	s_ashr_i32 s11, s10, 31
	s_lshl_b64 s[44:45], s[10:11], 20
	s_add_u32 s44, s79, s44
	s_addc_u32 s45, s82, s45
	s_and_b64 s[46:47], s[40:41], exec
	s_cselect_b32 s11, s45, s13
	s_cselect_b32 s15, s44, s12
	s_add_u32 s36, s36, 0x80080
	s_addc_u32 s37, s37, 0
	s_add_u32 s68, s12, 0x100
	v_mov_b32_e32 v0, 0
	s_addc_u32 s69, s13, 0
	s_mov_b32 s74, -2
	v_mov_b32_e32 v1, v0
	v_mov_b32_e32 v2, v0
	v_mov_b32_e32 v3, v0
	v_mov_b32_e32 v4, v0
	v_mov_b32_e32 v5, v0
	v_mov_b32_e32 v6, v0
	v_mov_b32_e32 v7, v0
	v_mov_b32_e32 v18, v0
	v_mov_b32_e32 v19, v0
	v_mov_b32_e32 v20, v0
	v_mov_b32_e32 v21, v0
	v_mov_b32_e32 v22, v0
	v_mov_b32_e32 v23, v0
	v_mov_b32_e32 v24, v0
	v_mov_b32_e32 v25, v0
	v_mov_b32_e32 v34, v0
	v_mov_b32_e32 v35, v0
	v_mov_b32_e32 v36, v0
	v_mov_b32_e32 v37, v0
	v_mov_b32_e32 v38, v0
	v_mov_b32_e32 v39, v0
	v_mov_b32_e32 v40, v0
	v_mov_b32_e32 v41, v0
	v_mov_b32_e32 v50, v0
	v_mov_b32_e32 v51, v0
	v_mov_b32_e32 v52, v0
	v_mov_b32_e32 v53, v0
	v_mov_b32_e32 v54, v0
	v_mov_b32_e32 v55, v0
	v_mov_b32_e32 v56, v0
	v_mov_b32_e32 v57, v0
	v_mov_b32_e32 v8, v0
	v_mov_b32_e32 v9, v0
	v_mov_b32_e32 v10, v0
	v_mov_b32_e32 v11, v0
	v_mov_b32_e32 v12, v0
	v_mov_b32_e32 v13, v0
	v_mov_b32_e32 v14, v0
	v_mov_b32_e32 v15, v0
	v_mov_b32_e32 v26, v0
	v_mov_b32_e32 v27, v0
	v_mov_b32_e32 v28, v0
	v_mov_b32_e32 v29, v0
	v_mov_b32_e32 v30, v0
	v_mov_b32_e32 v31, v0
	v_mov_b32_e32 v32, v0
	v_mov_b32_e32 v33, v0
	v_mov_b32_e32 v42, v0
	v_mov_b32_e32 v43, v0
	v_mov_b32_e32 v44, v0
	v_mov_b32_e32 v45, v0
	v_mov_b32_e32 v46, v0
	v_mov_b32_e32 v47, v0
	v_mov_b32_e32 v48, v0
	v_mov_b32_e32 v49, v0
	v_mov_b32_e32 v58, v0
	v_mov_b32_e32 v59, v0
	v_mov_b32_e32 v60, v0
	v_mov_b32_e32 v61, v0
	v_mov_b32_e32 v62, v0
	v_mov_b32_e32 v63, v0
	v_mov_b32_e32 v64, v0
	v_mov_b32_e32 v65, v0
	v_mov_b32_e32 v66, v0
	v_mov_b32_e32 v67, v0
	v_mov_b32_e32 v68, v0
	v_mov_b32_e32 v69, v0
	v_mov_b32_e32 v70, v0
	v_mov_b32_e32 v71, v0
	v_mov_b32_e32 v72, v0
	v_mov_b32_e32 v73, v0
	v_mov_b32_e32 v82, v0
	v_mov_b32_e32 v83, v0
	v_mov_b32_e32 v84, v0
	v_mov_b32_e32 v85, v0
	v_mov_b32_e32 v86, v0
	v_mov_b32_e32 v87, v0
	v_mov_b32_e32 v88, v0
	v_mov_b32_e32 v89, v0
	v_mov_b32_e32 v98, v0
	v_mov_b32_e32 v99, v0
	v_mov_b32_e32 v100, v0
	v_mov_b32_e32 v101, v0
	v_mov_b32_e32 v102, v0
	v_mov_b32_e32 v103, v0
	v_mov_b32_e32 v104, v0
	v_mov_b32_e32 v105, v0
	v_mov_b32_e32 v114, v0
	v_mov_b32_e32 v115, v0
	v_mov_b32_e32 v116, v0
	v_mov_b32_e32 v117, v0
	v_mov_b32_e32 v118, v0
	v_mov_b32_e32 v119, v0
	v_mov_b32_e32 v120, v0
	v_mov_b32_e32 v121, v0
	v_mov_b32_e32 v74, v0
	v_mov_b32_e32 v75, v0
	v_mov_b32_e32 v76, v0
	v_mov_b32_e32 v77, v0
	v_mov_b32_e32 v78, v0
	v_mov_b32_e32 v79, v0
	v_mov_b32_e32 v80, v0
	v_mov_b32_e32 v81, v0
	v_mov_b32_e32 v90, v0
	v_mov_b32_e32 v91, v0
	v_mov_b32_e32 v92, v0
	v_mov_b32_e32 v93, v0
	v_mov_b32_e32 v94, v0
	v_mov_b32_e32 v95, v0
	v_mov_b32_e32 v96, v0
	v_mov_b32_e32 v97, v0
	v_mov_b32_e32 v106, v0
	v_mov_b32_e32 v107, v0
	v_mov_b32_e32 v108, v0
	v_mov_b32_e32 v109, v0
	v_mov_b32_e32 v110, v0
	v_mov_b32_e32 v111, v0
	v_mov_b32_e32 v112, v0
	v_mov_b32_e32 v113, v0
	v_mov_b32_e32 v122, v0
	v_mov_b32_e32 v123, v0
	v_mov_b32_e32 v124, v0
	v_mov_b32_e32 v125, v0
	v_mov_b32_e32 v126, v0
	v_mov_b32_e32 v127, v0
	v_mov_b32_e32 v128, v0
	v_mov_b32_e32 v129, v0
	.p2align 6

; template <class Epi, class Sched, bool ALIGN_EPI = false, bool SP2 = false>
; __device__ __forceinline__ void gemm_phase(PG8_LAS unsigned char* lds, const Gemm g, const Sched& S, const Epi& E) {
;     ...
;         const bool has_next = S.next(ui + 1, nxt);
;         const char* nA = has_next ? PG8_UA(nxt) : cA; const char* nB = has_next ? PG8_UB(nxt) : cB;
;         for (int t = 0; t < nt; t += 2) {
;             const bool last = (t == nt - 2);
;             const char* a1 = cA + (size_t)(t + 1) * kstep;
;             const char* a2 = last ? nA : cA + (size_t)(t + 2) * kstep; const char* b2 = last ? nB : cB + (size_t)(t + 2) * kstep;
;     ...
; #pragma unroll
;         for (int a = 0; a < 2; ++a)
; #pragma unroll
;             for (int b = 0; b < 2; ++b)
; #pragma unroll
;                 for (int m = 0; m < 4; ++m)
; #pragma unroll
;                     for (int n = 0; n < 2; ++n) acc[a][b][m][n] = (f32x4){0.f, 0.f, 0.f, 0.f};
.LBB0_1222:
	s_ashr_i32 s45, s44, 31
	s_lshl_b64 s[6:7], s[74:75], 22
	s_lshl_b64 s[8:9], s[44:45], 19
	s_add_u32 s8, s10, s8
	s_addc_u32 s9, s11, s9
	s_add_u32 s84, s8, s6
	s_addc_u32 s85, s9, s7
	s_and_b64 s[6:7], s[76:77], exec
	s_cselect_b32 s6, s85, s5
	s_cselect_b32 s7, s84, s4
	s_add_u32 s8, s4, 0x100
	v_mov_b32_e32 v0, 0
	s_addc_u32 s9, s5, 0
	s_mov_b32 s21, -2
	v_mov_b32_e32 v1, v0
	v_mov_b32_e32 v2, v0
	v_mov_b32_e32 v3, v0
	v_mov_b32_e32 v4, v0
	v_mov_b32_e32 v5, v0
	v_mov_b32_e32 v6, v0
	v_mov_b32_e32 v7, v0
	v_mov_b32_e32 v18, v0
	v_mov_b32_e32 v19, v0
	v_mov_b32_e32 v20, v0
	v_mov_b32_e32 v21, v0
	v_mov_b32_e32 v22, v0
	v_mov_b32_e32 v23, v0
	v_mov_b32_e32 v24, v0
	v_mov_b32_e32 v25, v0
	v_mov_b32_e32 v34, v0
	v_mov_b32_e32 v35, v0
	v_mov_b32_e32 v36, v0
	v_mov_b32_e32 v37, v0
	v_mov_b32_e32 v38, v0
	v_mov_b32_e32 v39, v0
	v_mov_b32_e32 v40, v0
	v_mov_b32_e32 v41, v0
	v_mov_b32_e32 v50, v0
	v_mov_b32_e32 v51, v0
	v_mov_b32_e32 v52, v0
	v_mov_b32_e32 v53, v0
	v_mov_b32_e32 v54, v0
	v_mov_b32_e32 v55, v0
	v_mov_b32_e32 v56, v0
	v_mov_b32_e32 v57, v0
	v_mov_b32_e32 v8, v0
	v_mov_b32_e32 v9, v0
	v_mov_b32_e32 v10, v0
	v_mov_b32_e32 v11, v0
	v_mov_b32_e32 v12, v0
	v_mov_b32_e32 v13, v0
	v_mov_b32_e32 v14, v0
	v_mov_b32_e32 v15, v0
	v_mov_b32_e32 v26, v0
	v_mov_b32_e32 v27, v0
	v_mov_b32_e32 v28, v0
	v_mov_b32_e32 v29, v0
	v_mov_b32_e32 v30, v0
	v_mov_b32_e32 v31, v0
	v_mov_b32_e32 v32, v0
	v_mov_b32_e32 v33, v0
	v_mov_b32_e32 v42, v0
	v_mov_b32_e32 v43, v0
	v_mov_b32_e32 v44, v0
	v_mov_b32_e32 v45, v0
	v_mov_b32_e32 v46, v0
	v_mov_b32_e32 v47, v0
	v_mov_b32_e32 v48, v0
	v_mov_b32_e32 v49, v0
	v_mov_b32_e32 v58, v0
	v_mov_b32_e32 v59, v0
	v_mov_b32_e32 v60, v0
	v_mov_b32_e32 v61, v0
	v_mov_b32_e32 v62, v0
	v_mov_b32_e32 v63, v0
	v_mov_b32_e32 v64, v0
	v_mov_b32_e32 v65, v0
	v_mov_b32_e32 v66, v0
	v_mov_b32_e32 v67, v0
	v_mov_b32_e32 v68, v0
	v_mov_b32_e32 v69, v0
	v_mov_b32_e32 v70, v0
	v_mov_b32_e32 v71, v0
	v_mov_b32_e32 v72, v0
	v_mov_b32_e32 v73, v0
	v_mov_b32_e32 v82, v0
	v_mov_b32_e32 v83, v0
	v_mov_b32_e32 v84, v0
	v_mov_b32_e32 v85, v0
	v_mov_b32_e32 v86, v0
	v_mov_b32_e32 v87, v0
	v_mov_b32_e32 v88, v0
	v_mov_b32_e32 v89, v0
	v_mov_b32_e32 v98, v0
	v_mov_b32_e32 v99, v0
	v_mov_b32_e32 v100, v0
	v_mov_b32_e32 v101, v0
	v_mov_b32_e32 v102, v0
	v_mov_b32_e32 v103, v0
	v_mov_b32_e32 v104, v0
	v_mov_b32_e32 v105, v0
	v_mov_b32_e32 v114, v0
	v_mov_b32_e32 v115, v0
	v_mov_b32_e32 v116, v0
	v_mov_b32_e32 v117, v0
	v_mov_b32_e32 v118, v0
	v_mov_b32_e32 v119, v0
	v_mov_b32_e32 v120, v0
	v_mov_b32_e32 v121, v0
	v_mov_b32_e32 v74, v0
	v_mov_b32_e32 v75, v0
	v_mov_b32_e32 v76, v0
	v_mov_b32_e32 v77, v0
	v_mov_b32_e32 v78, v0
	v_mov_b32_e32 v79, v0
	v_mov_b32_e32 v80, v0
	v_mov_b32_e32 v81, v0
	v_mov_b32_e32 v90, v0
	v_mov_b32_e32 v91, v0
	v_mov_b32_e32 v92, v0
	v_mov_b32_e32 v93, v0
	v_mov_b32_e32 v94, v0
	v_mov_b32_e32 v95, v0
	v_mov_b32_e32 v96, v0
	v_mov_b32_e32 v97, v0
	v_mov_b32_e32 v106, v0
	v_mov_b32_e32 v107, v0
	v_mov_b32_e32 v108, v0
	v_mov_b32_e32 v109, v0
	v_mov_b32_e32 v110, v0
	v_mov_b32_e32 v111, v0
	v_mov_b32_e32 v112, v0
	v_mov_b32_e32 v113, v0
	v_mov_b32_e32 v122, v0
	v_mov_b32_e32 v123, v0
	v_mov_b32_e32 v124, v0
	v_mov_b32_e32 v125, v0
	v_mov_b32_e32 v126, v0
	v_mov_b32_e32 v127, v0
	v_mov_b32_e32 v128, v0
	v_mov_b32_e32 v129, v0
	.p2align 6

; template <class Epi, class Sched, bool ALIGN_EPI = false, bool SP2 = false>
; __device__ __forceinline__ void gemm_phase(PG8_LAS unsigned char* lds, const Gemm g, const Sched& S, const Epi& E) {
;     ...
;         const bool has_next = S.next(ui + 1, nxt);
;         const char* nA = has_next ? PG8_UA(nxt) : cA; const char* nB = has_next ? PG8_UB(nxt) : cB;
;         for (int t = 0; t < nt; t += 2) {
;             const bool last = (t == nt - 2);
;             const char* a1 = cA + (size_t)(t + 1) * kstep;
;             const char* a2 = last ? nA : cA + (size_t)(t + 2) * kstep; const char* b2 = last ? nB : cB + (size_t)(t + 2) * kstep;
;     ...
; #pragma unroll
;         for (int a = 0; a < 2; ++a)
; #pragma unroll
;             for (int b = 0; b < 2; ++b)
; #pragma unroll
;                 for (int m = 0; m < 4; ++m)
; #pragma unroll
;                     for (int n = 0; n < 2; ++n) acc[a][b][m][n] = (f32x4){0.f, 0.f, 0.f, 0.f};
.LBB0_1371:
	s_ashr_i32 s7, s6, 31
	s_lshl_b64 s[10:11], s[6:7], 20
	s_add_u32 s10, s18, s10
	s_addc_u32 s11, s19, s11
	s_and_b64 s[14:15], s[14:15], exec
	s_cselect_b32 s7, s11, s13
	s_cselect_b32 s14, s10, s12
	s_add_u32 s15, s12, 0x100
	v_mov_b32_e32 v0, 0
	s_addc_u32 s29, s13, 0
	s_mov_b32 s30, -2
	v_mov_b32_e32 v1, v0
	v_mov_b32_e32 v2, v0
	v_mov_b32_e32 v3, v0
	v_mov_b32_e32 v4, v0
	v_mov_b32_e32 v5, v0
	v_mov_b32_e32 v6, v0
	v_mov_b32_e32 v7, v0
	v_mov_b32_e32 v12, v0
	v_mov_b32_e32 v13, v0
	v_mov_b32_e32 v14, v0
	v_mov_b32_e32 v15, v0
	v_mov_b32_e32 v22, v0
	v_mov_b32_e32 v23, v0
	v_mov_b32_e32 v24, v0
	v_mov_b32_e32 v25, v0
	v_mov_b32_e32 v30, v0
	v_mov_b32_e32 v31, v0
	v_mov_b32_e32 v32, v0
	v_mov_b32_e32 v33, v0
	v_mov_b32_e32 v38, v0
	v_mov_b32_e32 v39, v0
	v_mov_b32_e32 v40, v0
	v_mov_b32_e32 v41, v0
	v_mov_b32_e32 v46, v0
	v_mov_b32_e32 v47, v0
	v_mov_b32_e32 v48, v0
	v_mov_b32_e32 v49, v0
	v_mov_b32_e32 v54, v0
	v_mov_b32_e32 v55, v0
	v_mov_b32_e32 v56, v0
	v_mov_b32_e32 v57, v0
	v_mov_b32_e32 v8, v0
	v_mov_b32_e32 v9, v0
	v_mov_b32_e32 v10, v0
	v_mov_b32_e32 v11, v0
	v_mov_b32_e32 v18, v0
	v_mov_b32_e32 v19, v0
	v_mov_b32_e32 v20, v0
	v_mov_b32_e32 v21, v0
	v_mov_b32_e32 v26, v0
	v_mov_b32_e32 v27, v0
	v_mov_b32_e32 v28, v0
	v_mov_b32_e32 v29, v0
	v_mov_b32_e32 v34, v0
	v_mov_b32_e32 v35, v0
	v_mov_b32_e32 v36, v0
	v_mov_b32_e32 v37, v0
	v_mov_b32_e32 v42, v0
	v_mov_b32_e32 v43, v0
	v_mov_b32_e32 v44, v0
	v_mov_b32_e32 v45, v0
	v_mov_b32_e32 v50, v0
	v_mov_b32_e32 v51, v0
	v_mov_b32_e32 v52, v0
	v_mov_b32_e32 v53, v0
	v_mov_b32_e32 v58, v0
	v_mov_b32_e32 v59, v0
	v_mov_b32_e32 v60, v0
	v_mov_b32_e32 v61, v0
	v_mov_b32_e32 v62, v0
	v_mov_b32_e32 v63, v0
	v_mov_b32_e32 v64, v0
	v_mov_b32_e32 v65, v0
	v_mov_b32_e32 v66, v0
	v_mov_b32_e32 v67, v0
	v_mov_b32_e32 v68, v0
	v_mov_b32_e32 v69, v0
	v_mov_b32_e32 v70, v0
	v_mov_b32_e32 v71, v0
	v_mov_b32_e32 v72, v0
	v_mov_b32_e32 v73, v0
	v_mov_b32_e32 v78, v0
	v_mov_b32_e32 v79, v0
	v_mov_b32_e32 v80, v0
	v_mov_b32_e32 v81, v0
	v_mov_b32_e32 v86, v0
	v_mov_b32_e32 v87, v0
	v_mov_b32_e32 v88, v0
	v_mov_b32_e32 v89, v0
	v_mov_b32_e32 v94, v0
	v_mov_b32_e32 v95, v0
	v_mov_b32_e32 v96, v0
	v_mov_b32_e32 v97, v0
	v_mov_b32_e32 v102, v0
	v_mov_b32_e32 v103, v0
	v_mov_b32_e32 v104, v0
	v_mov_b32_e32 v105, v0
	v_mov_b32_e32 v114, v0
	v_mov_b32_e32 v115, v0
	v_mov_b32_e32 v116, v0
	v_mov_b32_e32 v117, v0
	v_mov_b32_e32 v118, v0
	v_mov_b32_e32 v119, v0
	v_mov_b32_e32 v120, v0
	v_mov_b32_e32 v121, v0
	v_mov_b32_e32 v74, v0
	v_mov_b32_e32 v75, v0
	v_mov_b32_e32 v76, v0
	v_mov_b32_e32 v77, v0
	v_mov_b32_e32 v82, v0
	v_mov_b32_e32 v83, v0
	v_mov_b32_e32 v84, v0
	v_mov_b32_e32 v85, v0
	v_mov_b32_e32 v90, v0
	v_mov_b32_e32 v91, v0
	v_mov_b32_e32 v92, v0
	v_mov_b32_e32 v93, v0
	v_mov_b32_e32 v98, v0
	v_mov_b32_e32 v99, v0
	v_mov_b32_e32 v100, v0
	v_mov_b32_e32 v101, v0
	v_mov_b32_e32 v106, v0
	v_mov_b32_e32 v107, v0
	v_mov_b32_e32 v108, v0
	v_mov_b32_e32 v109, v0
	v_mov_b32_e32 v110, v0
	v_mov_b32_e32 v111, v0
	v_mov_b32_e32 v112, v0
	v_mov_b32_e32 v113, v0
	v_mov_b32_e32 v122, v0
	v_mov_b32_e32 v123, v0
	v_mov_b32_e32 v124, v0
	v_mov_b32_e32 v125, v0
	v_mov_b32_e32 v126, v0
	v_mov_b32_e32 v127, v0
	v_mov_b32_e32 v128, v0
	v_mov_b32_e32 v129, v0
	.p2align 6

; template <class Epi, class Sched, bool ALIGN_EPI = false, bool SP2 = false>
; __device__ __forceinline__ void gemm_phase(PG8_LAS unsigned char* lds, const Gemm g, const Sched& S, const Epi& E) {
;     ...
;         const bool has_next = S.next(ui + 1, nxt);
;         const char* nA = has_next ? PG8_UA(nxt) : cA; const char* nB = has_next ? PG8_UB(nxt) : cB;
;         for (int t = 0; t < nt; t += 2) {
;             const bool last = (t == nt - 2);
;             const char* a1 = cA + (size_t)(t + 1) * kstep;
;             const char* a2 = last ? nA : cA + (size_t)(t + 2) * kstep; const char* b2 = last ? nB : cB + (size_t)(t + 2) * kstep;
;     ...
; #pragma unroll
;         for (int a = 0; a < 2; ++a)
; #pragma unroll
;             for (int b = 0; b < 2; ++b)
; #pragma unroll
;                 for (int m = 0; m < 4; ++m)
; #pragma unroll
;                     for (int n = 0; n < 2; ++n) acc[a][b][m][n] = (f32x4){0.f, 0.f, 0.f, 0.f};
.LBB0_1505:
	s_ashr_i32 s43, s42, 31
	s_lshl_b64 s[46:47], s[42:43], 20
	s_add_u32 s46, s3, s46
	s_addc_u32 s47, s14, s47
	s_and_b64 s[74:75], s[44:45], exec
	s_cselect_b32 s43, s47, s77
	s_cselect_b32 s82, s46, s76
	s_ashr_i32 s11, s10, 31
	s_lshl_b64 s[74:75], s[10:11], 20
	s_add_u32 s74, s15, s74
	s_addc_u32 s75, s17, s75
	s_and_b64 s[84:85], s[44:45], exec
	s_cselect_b32 s11, s75, s13
	s_cselect_b32 s83, s74, s12
	s_add_u32 s76, s76, 0x80080
	s_addc_u32 s77, s77, 0
	s_add_u32 s88, s12, 0x100
	v_mov_b32_e32 v0, 0
	s_addc_u32 s89, s13, 0
	s_mov_b32 vcc_lo, -2
	v_mov_b32_e32 v1, v0
	v_mov_b32_e32 v2, v0
	v_mov_b32_e32 v3, v0
	v_mov_b32_e32 v4, v0
	v_mov_b32_e32 v5, v0
	v_mov_b32_e32 v6, v0
	v_mov_b32_e32 v7, v0
	v_mov_b32_e32 v8, v0
	v_mov_b32_e32 v9, v0
	v_mov_b32_e32 v10, v0
	v_mov_b32_e32 v11, v0
	v_mov_b32_e32 v12, v0
	v_mov_b32_e32 v13, v0
	v_mov_b32_e32 v14, v0
	v_mov_b32_e32 v15, v0
	v_mov_b32_e32 v26, v0
	v_mov_b32_e32 v27, v0
	v_mov_b32_e32 v28, v0
	v_mov_b32_e32 v29, v0
	v_mov_b32_e32 v30, v0
	v_mov_b32_e32 v31, v0
	v_mov_b32_e32 v32, v0
	v_mov_b32_e32 v33, v0
	v_mov_b32_e32 v42, v0
	v_mov_b32_e32 v43, v0
	v_mov_b32_e32 v44, v0
	v_mov_b32_e32 v45, v0
	v_mov_b32_e32 v46, v0
	v_mov_b32_e32 v47, v0
	v_mov_b32_e32 v48, v0
	v_mov_b32_e32 v49, v0
	v_mov_b32_e32 v18, v0
	v_mov_b32_e32 v19, v0
	v_mov_b32_e32 v20, v0
	v_mov_b32_e32 v21, v0
	v_mov_b32_e32 v22, v0
	v_mov_b32_e32 v23, v0
	v_mov_b32_e32 v24, v0
	v_mov_b32_e32 v25, v0
	v_mov_b32_e32 v34, v0
	v_mov_b32_e32 v35, v0
	v_mov_b32_e32 v36, v0
	v_mov_b32_e32 v37, v0
	v_mov_b32_e32 v38, v0
	v_mov_b32_e32 v39, v0
	v_mov_b32_e32 v40, v0
	v_mov_b32_e32 v41, v0
	v_mov_b32_e32 v50, v0
	v_mov_b32_e32 v51, v0
	v_mov_b32_e32 v52, v0
	v_mov_b32_e32 v53, v0
	v_mov_b32_e32 v54, v0
	v_mov_b32_e32 v55, v0
	v_mov_b32_e32 v56, v0
	v_mov_b32_e32 v57, v0
	v_mov_b32_e32 v58, v0
	v_mov_b32_e32 v59, v0
	v_mov_b32_e32 v60, v0
	v_mov_b32_e32 v61, v0
	v_mov_b32_e32 v62, v0
	v_mov_b32_e32 v63, v0
	v_mov_b32_e32 v64, v0
	v_mov_b32_e32 v65, v0
	v_mov_b32_e32 v66, v0
	v_mov_b32_e32 v67, v0
	v_mov_b32_e32 v68, v0
	v_mov_b32_e32 v69, v0
	v_mov_b32_e32 v70, v0
	v_mov_b32_e32 v71, v0
	v_mov_b32_e32 v72, v0
	v_mov_b32_e32 v73, v0
	v_mov_b32_e32 v74, v0
	v_mov_b32_e32 v75, v0
	v_mov_b32_e32 v76, v0
	v_mov_b32_e32 v77, v0
	v_mov_b32_e32 v78, v0
	v_mov_b32_e32 v79, v0
	v_mov_b32_e32 v80, v0
	v_mov_b32_e32 v81, v0
	v_mov_b32_e32 v90, v0
	v_mov_b32_e32 v91, v0
	v_mov_b32_e32 v92, v0
	v_mov_b32_e32 v93, v0
	v_mov_b32_e32 v94, v0
	v_mov_b32_e32 v95, v0
	v_mov_b32_e32 v96, v0
	v_mov_b32_e32 v97, v0
	v_mov_b32_e32 v106, v0
	v_mov_b32_e32 v107, v0
	v_mov_b32_e32 v108, v0
	v_mov_b32_e32 v109, v0
	v_mov_b32_e32 v110, v0
	v_mov_b32_e32 v111, v0
	v_mov_b32_e32 v112, v0
	v_mov_b32_e32 v113, v0
	v_mov_b32_e32 v82, v0
	v_mov_b32_e32 v83, v0
	v_mov_b32_e32 v84, v0
	v_mov_b32_e32 v85, v0
	v_mov_b32_e32 v86, v0
	v_mov_b32_e32 v87, v0
	v_mov_b32_e32 v88, v0
	v_mov_b32_e32 v89, v0
	v_mov_b32_e32 v98, v0
	v_mov_b32_e32 v99, v0
	v_mov_b32_e32 v100, v0
	v_mov_b32_e32 v101, v0
	v_mov_b32_e32 v102, v0
	v_mov_b32_e32 v103, v0
	v_mov_b32_e32 v104, v0
	v_mov_b32_e32 v105, v0
	v_mov_b32_e32 v114, v0
	v_mov_b32_e32 v115, v0
	v_mov_b32_e32 v116, v0
	v_mov_b32_e32 v117, v0
	v_mov_b32_e32 v118, v0
	v_mov_b32_e32 v119, v0
	v_mov_b32_e32 v120, v0
	v_mov_b32_e32 v121, v0
	v_mov_b32_e32 v122, v0
	v_mov_b32_e32 v123, v0
	v_mov_b32_e32 v124, v0
	v_mov_b32_e32 v125, v0
	v_mov_b32_e32 v126, v0
	v_mov_b32_e32 v127, v0
	v_mov_b32_e32 v128, v0
	v_mov_b32_e32 v129, v0
	.p2align 6

; template <class Epi, class Sched, bool ALIGN_EPI = false, bool SP2 = false>
; __device__ __forceinline__ void gemm_phase(PG8_LAS unsigned char* lds, const Gemm g, const Sched& S, const Epi& E) {
;     ...
;         const bool has_next = S.next(ui + 1, nxt);
;         const char* nA = has_next ? PG8_UA(nxt) : cA; const char* nB = has_next ? PG8_UB(nxt) : cB;
;         for (int t = 0; t < nt; t += 2) {
;             const bool last = (t == nt - 2);
;             const char* a1 = cA + (size_t)(t + 1) * kstep;
;             const char* a2 = last ? nA : cA + (size_t)(t + 2) * kstep; const char* b2 = last ? nB : cB + (size_t)(t + 2) * kstep;
;     ...
; #pragma unroll
;         for (int a = 0; a < 2; ++a)
; #pragma unroll
;             for (int b = 0; b < 2; ++b)
; #pragma unroll
;                 for (int m = 0; m < 4; ++m)
; #pragma unroll
;                     for (int n = 0; n < 2; ++n) acc[a][b][m][n] = (f32x4){0.f, 0.f, 0.f, 0.f};
.LBB0_1650:
	s_add_u32 s35, s46, 0x100
	v_mov_b32_e32 v0, 0
	s_addc_u32 s83, s47, 0
	s_mov_b32 s85, -2
	v_mov_b32_e32 v1, v0
	v_mov_b32_e32 v2, v0
	v_mov_b32_e32 v3, v0
	v_mov_b32_e32 v4, v0
	v_mov_b32_e32 v5, v0
	v_mov_b32_e32 v6, v0
	v_mov_b32_e32 v7, v0
	v_mov_b32_e32 v12, v0
	v_mov_b32_e32 v13, v0
	v_mov_b32_e32 v14, v0
	v_mov_b32_e32 v15, v0
	v_mov_b32_e32 v22, v0
	v_mov_b32_e32 v23, v0
	v_mov_b32_e32 v24, v0
	v_mov_b32_e32 v25, v0
	v_mov_b32_e32 v30, v0
	v_mov_b32_e32 v31, v0
	v_mov_b32_e32 v32, v0
	v_mov_b32_e32 v33, v0
	v_mov_b32_e32 v38, v0
	v_mov_b32_e32 v39, v0
	v_mov_b32_e32 v40, v0
	v_mov_b32_e32 v41, v0
	v_mov_b32_e32 v46, v0
	v_mov_b32_e32 v47, v0
	v_mov_b32_e32 v48, v0
	v_mov_b32_e32 v49, v0
	v_mov_b32_e32 v54, v0
	v_mov_b32_e32 v55, v0
	v_mov_b32_e32 v56, v0
	v_mov_b32_e32 v57, v0
	v_mov_b32_e32 v8, v0
	v_mov_b32_e32 v9, v0
	v_mov_b32_e32 v10, v0
	v_mov_b32_e32 v11, v0
	v_mov_b32_e32 v18, v0
	v_mov_b32_e32 v19, v0
	v_mov_b32_e32 v20, v0
	v_mov_b32_e32 v21, v0
	v_mov_b32_e32 v26, v0
	v_mov_b32_e32 v27, v0
	v_mov_b32_e32 v28, v0
	v_mov_b32_e32 v29, v0
	v_mov_b32_e32 v34, v0
	v_mov_b32_e32 v35, v0
	v_mov_b32_e32 v36, v0
	v_mov_b32_e32 v37, v0
	v_mov_b32_e32 v42, v0
	v_mov_b32_e32 v43, v0
	v_mov_b32_e32 v44, v0
	v_mov_b32_e32 v45, v0
	v_mov_b32_e32 v50, v0
	v_mov_b32_e32 v51, v0
	v_mov_b32_e32 v52, v0
	v_mov_b32_e32 v53, v0
	v_mov_b32_e32 v58, v0
	v_mov_b32_e32 v59, v0
	v_mov_b32_e32 v60, v0
	v_mov_b32_e32 v61, v0
	v_mov_b32_e32 v62, v0
	v_mov_b32_e32 v63, v0
	v_mov_b32_e32 v64, v0
	v_mov_b32_e32 v65, v0
	v_mov_b32_e32 v66, v0
	v_mov_b32_e32 v67, v0
	v_mov_b32_e32 v68, v0
	v_mov_b32_e32 v69, v0
	v_mov_b32_e32 v70, v0
	v_mov_b32_e32 v71, v0
	v_mov_b32_e32 v72, v0
	v_mov_b32_e32 v73, v0
	v_mov_b32_e32 v78, v0
	v_mov_b32_e32 v79, v0
	v_mov_b32_e32 v80, v0
	v_mov_b32_e32 v81, v0
	v_mov_b32_e32 v86, v0
	v_mov_b32_e32 v87, v0
	v_mov_b32_e32 v88, v0
	v_mov_b32_e32 v89, v0
	v_mov_b32_e32 v94, v0
	v_mov_b32_e32 v95, v0
	v_mov_b32_e32 v96, v0
	v_mov_b32_e32 v97, v0
	v_mov_b32_e32 v102, v0
	v_mov_b32_e32 v103, v0
	v_mov_b32_e32 v104, v0
	v_mov_b32_e32 v105, v0
	v_mov_b32_e32 v114, v0
	v_mov_b32_e32 v115, v0
	v_mov_b32_e32 v116, v0
	v_mov_b32_e32 v117, v0
	v_mov_b32_e32 v118, v0
	v_mov_b32_e32 v119, v0
	v_mov_b32_e32 v120, v0
	v_mov_b32_e32 v121, v0
	v_mov_b32_e32 v74, v0
	v_mov_b32_e32 v75, v0
	v_mov_b32_e32 v76, v0
	v_mov_b32_e32 v77, v0
	v_mov_b32_e32 v82, v0
	v_mov_b32_e32 v83, v0
	v_mov_b32_e32 v84, v0
	v_mov_b32_e32 v85, v0
	v_mov_b32_e32 v90, v0
	v_mov_b32_e32 v91, v0
	v_mov_b32_e32 v92, v0
	v_mov_b32_e32 v93, v0
	v_mov_b32_e32 v98, v0
	v_mov_b32_e32 v99, v0
	v_mov_b32_e32 v100, v0
	v_mov_b32_e32 v101, v0
	v_mov_b32_e32 v106, v0
	v_mov_b32_e32 v107, v0
	v_mov_b32_e32 v108, v0
	v_mov_b32_e32 v109, v0
	v_mov_b32_e32 v110, v0
	v_mov_b32_e32 v111, v0
	v_mov_b32_e32 v112, v0
	v_mov_b32_e32 v113, v0
	v_mov_b32_e32 v122, v0
	v_mov_b32_e32 v123, v0
	v_mov_b32_e32 v124, v0
	v_mov_b32_e32 v125, v0
	v_mov_b32_e32 v126, v0
	v_mov_b32_e32 v127, v0
	v_mov_b32_e32 v128, v0
	v_mov_b32_e32 v129, v0
	.p2align 6
